# c24 + DIFF one-barrier half-step stagger: waves 4-7 take their per-step barrier (and issue their LDS-DMA share) at the start of the PV phase, waves 0-3 at the step head
# baseline (speedup 1.0000x reference)
.LBB0_1421:
	s_and_b32 s18, s18, 0x3fffffc0
	s_lshl_b32 s18, s18, 2
	s_add_i32 s18, s18, 0
	v_lshlrev_b32_e32 v2, 4, v39
	s_add_i32 s18, s18, 0x12300
	v_lshlrev_b32_e32 v1, 3, v39
	v_and_b32_e32 v2, 0xc0, v2
	v_lshlrev_b32_e32 v39, 1, v39
	v_and_or_b32 v2, v1, 24, v2
	v_and_b32_e32 v39, 32, v39
	v_and_b32_e32 v1, 0x100, v1
	s_cmp_lg_u32 0, -1
	v_or3_b32 v1, v2, v39, v1
	s_cselect_b32 s31, 0, 0
	v_add_u32_e32 v215, s31, v1
	v_max_f32_e32 v1, v5, v5
	v_max_f32_e32 v2, v4, v4
	v_max_f32_e32 v1, v2, v1
	v_max3_f32 v1, v1, v6, v7
	v_max3_f32 v1, v1, v8, v9
	v_max3_f32 v1, v1, v10, v11
	v_max3_f32 v1, v1, v12, v13
	v_max3_f32 v1, v1, v14, v15
	v_max3_f32 v1, v1, v16, v17
	v_max3_f32 v1, v1, v18, v19
	v_max3_f32 v1, v1, v20, v21
	v_max3_f32 v1, v1, v22, v23
	v_max3_f32 v1, v1, v24, v25
	v_max3_f32 v1, v1, v26, v27
	v_max3_f32 v1, v1, v28, v29
	v_max3_f32 v1, v1, v30, v31
	v_max3_f32 v1, v1, v32, v33
	v_max3_f32 v1, v1, v34, v35
	v_mov_b32_e32 v2, v1
	s_nop 1
	v_permlane32_swap_b32_e32 v1, v2
	v_max_f32_e32 v2, v2, v2
	v_max_f32_e32 v1, v1, v1
	v_max_f32_e32 v1, v1, v2
	s_ashr_i32 s31, s19, 31
	v_add_f32_e32 v221, 0, v1
	v_sub_f32_e32 v2, v4, v1
	v_sub_f32_e32 v4, v20, v1
	v_sub_f32_e32 v5, v5, v1
	v_sub_f32_e32 v20, v21, v1
	v_sub_f32_e32 v6, v6, v1
	v_sub_f32_e32 v21, v22, v1
	v_sub_f32_e32 v7, v7, v1
	v_sub_f32_e32 v22, v23, v1
	v_sub_f32_e32 v8, v8, v1
	v_sub_f32_e32 v23, v24, v1
	v_sub_f32_e32 v9, v9, v1
	v_sub_f32_e32 v24, v25, v1
	v_sub_f32_e32 v10, v10, v1
	v_sub_f32_e32 v25, v26, v1
	v_sub_f32_e32 v11, v11, v1
	v_sub_f32_e32 v26, v27, v1
	v_sub_f32_e32 v12, v12, v1
	v_sub_f32_e32 v27, v28, v1
	v_sub_f32_e32 v13, v13, v1
	v_sub_f32_e32 v28, v29, v1
	v_sub_f32_e32 v14, v14, v1
	v_sub_f32_e32 v29, v30, v1
	v_sub_f32_e32 v15, v15, v1
	v_sub_f32_e32 v30, v31, v1
	v_sub_f32_e32 v16, v16, v1
	v_sub_f32_e32 v31, v32, v1
	v_sub_f32_e32 v17, v17, v1
	v_sub_f32_e32 v32, v33, v1
	v_sub_f32_e32 v18, v18, v1
	v_sub_f32_e32 v33, v34, v1
	v_sub_f32_e32 v19, v19, v1
	v_sub_f32_e32 v1, v35, v1
	s_lshr_b32 s31, s31, 26
	v_exp_f32_e32 v96, v2
	v_exp_f32_e32 v80, v4
	v_exp_f32_e32 v97, v5
	v_exp_f32_e32 v81, v20
	v_exp_f32_e32 v98, v6
	v_exp_f32_e32 v82, v21
	v_exp_f32_e32 v99, v7
	v_exp_f32_e32 v83, v22
	v_exp_f32_e32 v100, v8
	v_exp_f32_e32 v84, v23
	v_exp_f32_e32 v101, v9
	v_exp_f32_e32 v85, v24
	v_exp_f32_e32 v102, v10
	v_exp_f32_e32 v86, v25
	v_exp_f32_e32 v103, v11
	v_exp_f32_e32 v87, v26
	v_exp_f32_e32 v104, v12
	v_exp_f32_e32 v88, v27
	v_exp_f32_e32 v105, v13
	v_exp_f32_e32 v89, v28
	v_exp_f32_e32 v106, v14
	v_exp_f32_e32 v90, v29
	v_exp_f32_e32 v107, v15
	v_exp_f32_e32 v91, v30
	v_exp_f32_e32 v108, v16
	v_exp_f32_e32 v92, v31
	v_exp_f32_e32 v109, v17
	v_exp_f32_e32 v93, v32
	v_exp_f32_e32 v110, v18
	v_exp_f32_e32 v94, v33
	v_exp_f32_e32 v111, v19
	v_exp_f32_e32 v95, v1
	s_add_i32 s19, s19, s31
	s_waitcnt vmcnt(0)
	v_mov_b32_e32 v14, v3
	v_mov_b32_e32 v15, v3
	s_ashr_i32 s31, s19, 6
	v_lshl_add_u64 v[190:191], s[34:35], 0, v[36:37]
	v_lshl_add_u32 v213, v38, 2, s18
	v_lshl_add_u32 v212, v0, 2, s18
	v_lshl_add_u64 v[194:195], s[40:41], 0, v[36:37]
	v_mov_b32_e32 v0, v3
	v_mov_b32_e32 v1, v3
	v_mov_b32_e32 v2, v3
	v_mov_b32_e32 v4, v3
	v_mov_b32_e32 v5, v3
	v_mov_b32_e32 v6, v3
	v_mov_b32_e32 v7, v3
	v_mov_b32_e32 v8, v3
	v_mov_b32_e32 v9, v3
	v_mov_b32_e32 v10, v3
	v_mov_b32_e32 v11, v3
	v_mov_b32_e32 v12, v3
	v_mov_b32_e32 v13, v3
	v_mov_b64_e32 v[30:31], v[14:15]
	v_mov_b64_e32 v[46:47], v[14:15]
	v_mov_b64_e32 v[62:63], v[14:15]
	v_mov_b64_e32 v[78:79], v[14:15]
	s_mov_b32 s44, 2
	s_mov_b32 s45, 4
	s_mov_b32 s69, 1
	s_mov_b32 s54, 0
	s_sub_i32 s19, 0, s31
	s_sub_i32 s64, 2, s31
	v_mov_b32_e32 v214, 0
	v_mov_b32_e32 v222, 1.0
	s_movk_i32 s65, 0x80
	v_mov_b64_e32 v[28:29], v[12:13]
	v_mov_b64_e32 v[26:27], v[10:11]
	v_mov_b64_e32 v[24:25], v[8:9]
	v_mov_b64_e32 v[22:23], v[6:7]
	v_mov_b64_e32 v[20:21], v[4:5]
	v_mov_b64_e32 v[18:19], v[2:3]
	v_mov_b64_e32 v[16:17], v[0:1]
	v_mov_b64_e32 v[44:45], v[12:13]
	v_mov_b64_e32 v[42:43], v[10:11]
	v_mov_b64_e32 v[40:41], v[8:9]
	v_mov_b64_e32 v[38:39], v[6:7]
	v_mov_b64_e32 v[36:37], v[4:5]
	v_mov_b64_e32 v[34:35], v[2:3]
	v_mov_b64_e32 v[32:33], v[0:1]
	v_mov_b64_e32 v[60:61], v[12:13]
	v_mov_b64_e32 v[58:59], v[10:11]
	v_mov_b64_e32 v[56:57], v[8:9]
	v_mov_b64_e32 v[54:55], v[6:7]
	v_mov_b64_e32 v[52:53], v[4:5]
	v_mov_b64_e32 v[50:51], v[2:3]
	v_mov_b64_e32 v[48:49], v[0:1]
	v_mov_b64_e32 v[76:77], v[12:13]
	v_mov_b64_e32 v[74:75], v[10:11]
	v_mov_b64_e32 v[72:73], v[8:9]
	v_mov_b64_e32 v[70:71], v[6:7]
	v_mov_b64_e32 v[68:69], v[4:5]
	v_mov_b64_e32 v[66:67], v[2:3]
	v_mov_b64_e32 v[64:65], v[0:1]
	s_waitcnt vmcnt(0)
	s_barrier
	v_readlane_b32 s99, v244, 15
	s_nop 3
.LBB0_1422:
	s_cmp_ge_u32 s99, 0x100
	s_cbranch_scc1 .Lst_a_odd
	s_barrier
.Lst_a_odd:
	s_lshl_b32 s18, s44, 14
	s_add_i32 s52, s81, s18
	s_mov_b32 m0, s52
	v_lshl_add_u64 v[0:1], v[194:195], 0, s[14:15]
	s_cmp_ge_u32 s99, 0x100
	s_cbranch_scc1 .Lst_h_odd0
	global_load_lds_dwordx4 v[194:195], off
.Lst_h_odd0:
	s_add_i32 m0, s52, 0x2000
	s_mul_i32 s52, s54, 0x2100
	s_add_i32 s52, s22, s52
	s_mov_b32 s100, s52
	s_cmp_ge_u32 s99, 0x100
	s_cbranch_scc1 .Lst_h_odd1
	global_load_lds_dwordx4 v[0:1], off
.Lst_h_odd1:
	s_add_i32 m0, s52, 0xc000
	s_add_i32 s52, s45, -1
	s_cmp_lt_u32 s52, s2
	s_cselect_b32 s55, s52, s3
	s_lshl_b32 s56, s55, 6
	s_mov_b32 s101, s56
	v_mad_u64_u32 v[0:1], s[52:53], s56, v209, v[192:193]
	v_lshl_add_u64 v[0:1], v[0:1], 0, s[10:11]
	s_cmp_ge_u32 s99, 0x100
	s_cbranch_scc1 .Lst_h_odd2
	global_load_lds_dwordx4 v[0:1], off
.Lst_h_odd2:
	s_mul_i32 s52, s55, 0x60000
	s_mul_hi_u32 s53, s56, 0x1800
	s_mul_i32 s55, s69, 0x2100
	s_add_i32 s71, s55, 0
	s_sub_i32 s55, s65, 64
	v_cvt_f32_u32_e32 v0, s55
	v_add_u32_e32 v166, s71, v220
	v_add_u32_e32 v167, s71, v217
	ds_read_b128 v[4:7], v166 offset:49152
	ds_read_b128 v[8:11], v167 offset:49152
	v_sub_f32_e32 v196, v0, v161
	v_fma_f32 v0, v210, v196, -v221
	v_cvt_pk_bf16_f32 v1, v0, v3
	v_lshlrev_b32_e32 v1, 16, v1
	v_sub_f32_e32 v0, v0, v1
	v_cvt_pk_bf16_f32 v2, v0, v3
	v_lshlrev_b32_e32 v2, 16, v2
	v_sub_f32_e32 v0, v0, v2
	v_cvt_pk_bf16_f32 v1, v1, v2
	v_cvt_pk_bf16_f32 v0, v0, v3
	s_nop 0
	v_cndmask_b32_e64 v2, 0, v0, s[4:5]
	v_cndmask_b32_e64 v0, 0, v160, s[4:5]
	v_cndmask_b32_e64 v1, 0, v1, s[4:5]
	s_nop 1
	v_mfma_f32_32x32x16_bf16 v[128:143], v[248:251], v[0:3], 0
	v_add_f32_e32 v226, v96, v97
	v_add_f32_e32 v226, v98, v226
	v_add_f32_e32 v226, v99, v226
	v_add_f32_e32 v226, v100, v226
	v_mfma_f32_32x32x16_bf16 v[112:127], v[252:255], v[0:3], 0
	v_add_f32_e32 v1, v101, v226
	v_add_f32_e32 v1, v102, v1
	s_waitcnt lgkmcnt(0)
	v_mfma_f32_32x32x16_bf16 v[128:143], v[8:11], v[156:159], v[128:143]
	v_add_f32_e32 v1, v103, v1
	v_add_f32_e32 v1, v104, v1
	v_add_f32_e32 v1, v105, v1
	v_add_f32_e32 v1, v106, v1
	v_add_f32_e32 v1, v107, v1
	v_add_f32_e32 v1, v108, v1
	v_add_f32_e32 v1, v109, v1
	v_mfma_f32_32x32x16_bf16 v[112:127], v[4:7], v[156:159], v[112:127]
	ds_read_b128 v[4:7], v166 offset:51264
	ds_read_b128 v[8:11], v167 offset:51264
	v_add_f32_e32 v1, v110, v1
	v_add_f32_e32 v1, v111, v1
	v_add_f32_e32 v1, v80, v1
	v_add_f32_e32 v1, v81, v1
	v_add_f32_e32 v1, v82, v1
	v_add_f32_e32 v1, v83, v1
	s_waitcnt lgkmcnt(0)
	v_mfma_f32_32x32x16_bf16 v[128:143], v[8:11], v[152:155], v[128:143]
	v_add_f32_e32 v1, v84, v1
	v_add_f32_e32 v1, v85, v1
	v_add_f32_e32 v1, v86, v1
	v_add_f32_e32 v1, v87, v1
	v_add_f32_e32 v1, v88, v1
	v_add_f32_e32 v1, v89, v1
	v_add_f32_e32 v1, v90, v1
	v_mfma_f32_32x32x16_bf16 v[112:127], v[4:7], v[152:155], v[112:127]
	ds_read_b128 v[4:7], v166 offset:53376
	ds_read_b128 v[8:11], v167 offset:53376
	v_add_f32_e32 v1, v91, v1
	v_add_f32_e32 v1, v92, v1
	v_add_f32_e32 v1, v93, v1
	v_add_f32_e32 v1, v94, v1
	v_add_f32_e32 v223, v95, v1
	v_mov_b32_e32 v224, v223
	s_waitcnt lgkmcnt(0)
	v_mfma_f32_32x32x16_bf16 v[128:143], v[8:11], v[148:151], v[128:143]
	v_permlane32_swap_b32_e32 v223, v224
	v_mfma_f32_32x32x16_bf16 v[112:127], v[4:7], v[148:151], v[112:127]
	ds_read_b128 v[4:7], v166 offset:55488
	ds_read_b128 v[8:11], v167 offset:55488
	v_cvt_pk_bf16_f32 v166, v96, v97
	v_cvt_pk_bf16_f32 v167, v98, v99
	v_cvt_pk_bf16_f32 v168, v100, v101
	v_cvt_pk_bf16_f32 v169, v102, v103
	v_cvt_pk_bf16_f32 v12, v104, v105
	v_cvt_pk_bf16_f32 v13, v106, v107
	s_waitcnt lgkmcnt(0)
	v_mfma_f32_32x32x16_bf16 v[128:143], v[8:11], v[144:147], v[128:143]
	v_cvt_pk_bf16_f32 v14, v108, v109
	v_cvt_pk_bf16_f32 v15, v110, v111
	v_cvt_pk_bf16_f32 v8, v80, v81
	v_cvt_pk_bf16_f32 v9, v82, v83
	v_cvt_pk_bf16_f32 v10, v84, v85
	v_cvt_pk_bf16_f32 v11, v86, v87
	v_mfma_f32_32x32x16_bf16 v[112:127], v[4:7], v[144:147], v[112:127]
	v_cvt_pk_bf16_f32 v4, v88, v89
	v_cvt_pk_bf16_f32 v5, v90, v91
	v_cvt_pk_bf16_f32 v6, v92, v93
	v_cvt_pk_bf16_f32 v7, v94, v95
	v_lshl_add_u32 v1, s54, 14, v215
	ds_read_b64_tr_b16 v[182:183], v1 offset:0
	ds_read_b64_tr_b16 v[184:185], v1 offset:0x800
	ds_read_b64_tr_b16 v[178:179], v1 offset:0x1000
	ds_read_b64_tr_b16 v[180:181], v1 offset:0x1800
	s_add_i32 s70, s45, -3
	s_add_i32 s54, s19, s45
	ds_read_b64_tr_b16 v[174:175], v1 offset:0x2000
	s_cmp_eq_u32 s54, 3
	ds_read_b64_tr_b16 v[176:177], v1 offset:0x2800
	s_cselect_b64 s[54:55], -1, 0
	ds_read_b64_tr_b16 v[170:171], v1 offset:0x3000
	v_cndmask_b32_e64 v2, 0, 1, s[54:55]
	ds_read_b64_tr_b16 v[172:173], v1 offset:0x3800
	s_cmp_lt_i32 s70, s31
	s_cbranch_scc0 .Lold_odd
	v_max3_f32 v245, v128, v129, v130
	v_max3_f32 v246, v112, v113, v114
	v_max3_f32 v245, v245, v131, v132
	v_max3_f32 v246, v246, v115, v116
	v_max3_f32 v245, v245, v133, v134
	v_max3_f32 v246, v246, v117, v118
	v_max3_f32 v245, v245, v135, v136
	v_max3_f32 v246, v246, v119, v120
	v_max3_f32 v245, v245, v137, v138
	v_max3_f32 v246, v246, v121, v122
	v_max3_f32 v245, v245, v139, v140
	v_max3_f32 v246, v246, v123, v124
	v_max3_f32 v245, v245, v141, v142
	v_max3_f32 v246, v246, v125, v126
	v_max_f32_e32 v245, v245, v143
	v_max_f32_e32 v246, v246, v127
	v_max_f32_e32 v245, v245, v246
	v_mov_b32_e32 v246, v245
	s_nop 1
	v_permlane32_swap_b32_e32 v245, v246
	v_max_f32_e32 v245, v245, v246
	v_cmp_ge_f32_e32 vcc, s68, v245
	s_cmp_eq_u64 vcc, exec
	v_mov_b32_e32 v225, 1.0
	s_cbranch_scc0 .Lf_odd_resc
.Lf_odd_exp:
	s_cmp_lt_u32 s99, 0x100
	s_cbranch_scc1 .Lst_b_oddf
	s_waitcnt vmcnt(0)
	s_barrier
	s_lshl_b32 s98, s44, 14
	s_add_i32 s98, s81, s98
	s_mov_b32 m0, s98
	v_lshl_add_u64 v[226:227], v[194:195], 0, s[14:15]
	global_load_lds_dwordx4 v[194:195], off
	s_add_i32 m0, s98, 0x2000
	s_nop 0
	global_load_lds_dwordx4 v[226:227], off
	s_add_i32 m0, s100, 0xc000
	s_mov_b32 s98, s101
	v_mad_u64_u32 v[226:227], s[100:101], s98, v209, v[192:193]
	v_lshl_add_u64 v[226:227], v[226:227], 0, s[10:11]
	global_load_lds_dwordx4 v[226:227], off

.LBB0_1437:
	s_add_i32 s54, s44, 1
	s_cmp_lg_u32 s44, 2
	s_cselect_b32 s67, s54, 0
	s_cmp_ge_u32 s99, 0x100
	s_cbranch_scc1 .Lst_a_even
	s_waitcnt vmcnt(0)
	s_barrier
.Lst_a_even:
	s_lshl_b32 s66, s67, 14
	s_add_i32 s54, s81, s66
	v_lshl_add_u64 v[4:5], v[190:191], 0, s[52:53]
	v_lshl_add_u64 v[242:243], v[190:191], 0, s[52:53]
	s_mov_b32 m0, s54
	s_add_i32 s52, s71, s82
	s_cmp_ge_u32 s99, 0x100
	s_cbranch_scc1 .Lst_h_even0
	global_load_lds_dwordx4 v[4:5], off
.Lst_h_even0:
	v_lshl_add_u64 v[4:5], v[4:5], 0, s[14:15]
	s_add_i32 m0, s54, 0x2000
	s_add_i32 s52, s52, s27
	s_mov_b32 s100, s52
	s_cmp_ge_u32 s99, 0x100
	s_cbranch_scc1 .Lst_h_even1
	global_load_lds_dwordx4 v[4:5], off
.Lst_h_even1:
	s_add_i32 m0, s52, 0xc000
	s_cmp_ge_u32 s45, s2
	s_cselect_b64 s[52:53], -1, 0
	s_cmp_lt_u32 s45, s2
	s_cselect_b32 s54, s45, s3
	s_lshl_b32 s54, s54, 6
	s_mov_b32 s101, s54
	v_mad_u64_u32 v[4:5], s[54:55], s54, v209, v[192:193]
	v_lshl_add_u64 v[4:5], v[4:5], 0, s[10:11]
	s_cmp_ge_u32 s99, 0x100
	s_cbranch_scc1 .Lst_h_even2
	global_load_lds_dwordx4 v[4:5], off
.Lst_h_even2:
	v_cvt_f32_u32_e32 v1, s65
	s_mul_i32 s54, s44, 0x2100
	s_add_i32 s54, s54, 0
	v_add_u32_e32 v166, s54, v220
	v_sub_f32_e32 v196, v1, v161
	v_add_u32_e32 v167, s54, v217
	v_fma_f32 v1, v210, v196, -v221
	ds_read_b128 v[4:7], v166 offset:49152
	ds_read_b128 v[8:11], v167 offset:49152
	v_cvt_pk_bf16_f32 v2, v1, v3
	v_lshlrev_b32_e32 v2, 16, v2
	v_sub_f32_e32 v1, v1, v2
	v_cvt_pk_bf16_f32 v12, v1, v3
	v_lshlrev_b32_e32 v12, 16, v12
	v_sub_f32_e32 v1, v1, v12
	v_cvt_pk_bf16_f32 v12, v2, v12
	v_cvt_pk_bf16_f32 v1, v1, v3
	s_nop 0
	v_cndmask_b32_e64 v2, 0, v1, s[4:5]
	v_cndmask_b32_e64 v1, 0, v12, s[4:5]
	s_nop 1
	v_mfma_f32_32x32x16_bf16 v[128:143], v[248:251], v[0:3], 0
	v_add_f32_e32 v226, v96, v97
	v_add_f32_e32 v226, v98, v226
	v_add_f32_e32 v226, v99, v226
	v_add_f32_e32 v226, v100, v226
	s_nop 0
	v_mfma_f32_32x32x16_bf16 v[112:127], v[252:255], v[0:3], 0
	v_add_f32_e32 v1, v101, v226
	v_add_f32_e32 v1, v102, v1
	s_waitcnt lgkmcnt(0)
	v_mfma_f32_32x32x16_bf16 v[128:143], v[8:11], v[156:159], v[128:143]
	v_add_f32_e32 v1, v103, v1
	v_add_f32_e32 v1, v104, v1
	v_add_f32_e32 v1, v105, v1
	v_add_f32_e32 v1, v106, v1
	v_add_f32_e32 v1, v107, v1
	v_add_f32_e32 v1, v108, v1
	v_add_f32_e32 v1, v109, v1
	v_mfma_f32_32x32x16_bf16 v[112:127], v[4:7], v[156:159], v[112:127]
	ds_read_b128 v[4:7], v166 offset:51264
	ds_read_b128 v[8:11], v167 offset:51264
	v_add_f32_e32 v1, v110, v1
	v_add_f32_e32 v1, v111, v1
	v_add_f32_e32 v1, v80, v1
	v_add_f32_e32 v1, v81, v1
	v_add_f32_e32 v1, v82, v1
	v_add_f32_e32 v1, v83, v1
	s_waitcnt lgkmcnt(0)
	v_mfma_f32_32x32x16_bf16 v[128:143], v[8:11], v[152:155], v[128:143]
	v_add_f32_e32 v1, v84, v1
	v_add_f32_e32 v1, v85, v1
	v_add_f32_e32 v1, v86, v1
	v_add_f32_e32 v1, v87, v1
	v_add_f32_e32 v1, v88, v1
	v_add_f32_e32 v1, v89, v1
	v_add_f32_e32 v1, v90, v1
	v_mfma_f32_32x32x16_bf16 v[112:127], v[4:7], v[152:155], v[112:127]
	ds_read_b128 v[4:7], v166 offset:53376
	ds_read_b128 v[8:11], v167 offset:53376
	v_add_f32_e32 v1, v91, v1
	v_add_f32_e32 v1, v92, v1
	v_add_f32_e32 v1, v93, v1
	v_add_f32_e32 v1, v94, v1
	v_add_f32_e32 v1, v95, v1
	v_mov_b32_e32 v2, v1
	s_waitcnt lgkmcnt(0)
	v_mfma_f32_32x32x16_bf16 v[128:143], v[8:11], v[148:151], v[128:143]
	v_permlane32_swap_b32_e32 v1, v2
	v_mfma_f32_32x32x16_bf16 v[112:127], v[4:7], v[148:151], v[112:127]
	ds_read_b128 v[4:7], v166 offset:55488
	ds_read_b128 v[8:11], v167 offset:55488
	v_cvt_pk_bf16_f32 v166, v96, v97
	v_cvt_pk_bf16_f32 v167, v98, v99
	v_cvt_pk_bf16_f32 v168, v100, v101
	v_cvt_pk_bf16_f32 v169, v102, v103
	v_cvt_pk_bf16_f32 v12, v104, v105
	v_cvt_pk_bf16_f32 v13, v106, v107
	s_waitcnt lgkmcnt(0)
	v_mfma_f32_32x32x16_bf16 v[128:143], v[8:11], v[144:147], v[128:143]
	v_cvt_pk_bf16_f32 v14, v108, v109
	v_cvt_pk_bf16_f32 v15, v110, v111
	v_cvt_pk_bf16_f32 v8, v80, v81
	v_cvt_pk_bf16_f32 v9, v82, v83
	v_cvt_pk_bf16_f32 v10, v84, v85
	v_cvt_pk_bf16_f32 v11, v86, v87
	v_mfma_f32_32x32x16_bf16 v[112:127], v[4:7], v[144:147], v[112:127]
	v_cvt_pk_bf16_f32 v4, v88, v89
	v_cvt_pk_bf16_f32 v5, v90, v91
	v_cvt_pk_bf16_f32 v6, v92, v93
	v_cvt_pk_bf16_f32 v7, v94, v95
	v_lshl_add_u32 v162, s69, 14, v215
	ds_read_b64_tr_b16 v[182:183], v162 offset:0
	ds_read_b64_tr_b16 v[184:185], v162 offset:0x800
	ds_read_b64_tr_b16 v[178:179], v162 offset:0x1000
	ds_read_b64_tr_b16 v[180:181], v162 offset:0x1800
	s_add_i32 s54, s64, s45
	ds_read_b64_tr_b16 v[174:175], v162 offset:0x2000
	s_cmp_eq_u32 s54, 4
	ds_read_b64_tr_b16 v[176:177], v162 offset:0x2800
	s_cselect_b64 s[54:55], -1, 0
	ds_read_b64_tr_b16 v[170:171], v162 offset:0x3000
	v_cndmask_b32_e64 v80, 0, 1, s[54:55]
	ds_read_b64_tr_b16 v[172:173], v162 offset:0x3800
	s_add_i32 s98, s70, 2
	s_cmp_le_i32 s98, s31
	s_cbranch_scc0 .Lold_even
	v_max3_f32 v245, v128, v129, v130
	v_max3_f32 v246, v112, v113, v114
	v_max3_f32 v245, v245, v131, v132
	v_max3_f32 v246, v246, v115, v116
	v_max3_f32 v245, v245, v133, v134
	v_max3_f32 v246, v246, v117, v118
	v_max3_f32 v245, v245, v135, v136
	v_max3_f32 v246, v246, v119, v120
	v_max3_f32 v245, v245, v137, v138
	v_max3_f32 v246, v246, v121, v122
	v_max3_f32 v245, v245, v139, v140
	v_max3_f32 v246, v246, v123, v124
	v_max3_f32 v245, v245, v141, v142
	v_max3_f32 v246, v246, v125, v126
	v_max_f32_e32 v245, v245, v143
	v_max_f32_e32 v246, v246, v127
	v_max_f32_e32 v245, v245, v246
	v_mov_b32_e32 v246, v245
	s_nop 1
	v_permlane32_swap_b32_e32 v245, v246
	v_max_f32_e32 v245, v245, v246
	v_cmp_ge_f32_e32 vcc, s68, v245
	s_cmp_eq_u64 vcc, exec
	v_mov_b32_e32 v196, 1.0
	s_cbranch_scc0 .Lf_even_resc
.Lf_even_exp:
	s_cmp_lt_u32 s99, 0x100
	s_cbranch_scc1 .Lst_b_evenf
	s_waitcnt vmcnt(0)
	s_barrier
	s_lshl_b32 s98, s67, 14
	s_add_i32 s98, s81, s98
	s_mov_b32 m0, s98
	s_nop 0
	global_load_lds_dwordx4 v[242:243], off
	v_lshl_add_u64 v[226:227], v[242:243], 0, s[14:15]
	s_add_i32 m0, s98, 0x2000
	s_nop 0
	global_load_lds_dwordx4 v[226:227], off
	s_add_i32 m0, s100, 0xc000
	s_mov_b32 s98, s101
	v_mad_u64_u32 v[226:227], s[100:101], s98, v209, v[192:193]
	v_lshl_add_u64 v[226:227], v[226:227], 0, s[10:11]
	global_load_lds_dwordx4 v[226:227], off

.LBB0_1452:
	v_add_f32_e32 v4, v223, v224
	s_add_i32 s54, s67, 1
	v_fmac_f32_e32 v4, v222, v214
	v_add_f32_e32 v214, v1, v2
	s_cmp_lg_u32 s67, 2
	v_fmac_f32_e32 v214, v4, v225
	s_cselect_b32 s55, s54, 0
	s_add_i32 s45, s45, 2
	s_addk_i32 s65, 0x80
	v_lshl_add_u64 v[194:195], v[194:195], 0, s[16:17]
	s_and_b64 vcc, exec, s[52:53]
	s_cmp_ge_u32 s99, 0x100
	s_cbranch_scc1 .Lst_tail
	s_waitcnt vmcnt(0)
.Lst_tail:
	s_cbranch_vccnz .Lrot10_exit
	s_mov_b32 s54, s44
	s_mov_b32 s69, s67
	s_mov_b32 s44, s55
	v_mov_b32_e32 v222, v196
	s_branch .LBB0_1422
.Lrot10_exit:
	s_waitcnt vmcnt(0)
	s_barrier
	s_branch .LBB0_1458
